# re-measure: hoisted rowss/sw loads in QKV/UV/FT epilogues (same bytes as v1)
# baseline (speedup 1.0000x reference)
; #define LAS __attribute__((address_space(3)))
; __global__ void __launch_bounds__(NTHR, 2) mk_fwd(Params p) {
;     extern __shared__ __attribute__((aligned(16))) unsigned char lds_raw[];
;     LAS unsigned char* lds = (LAS unsigned char*)lds_raw;
;     cg::grid_group grid = cg::this_grid();
;     unsigned char* ws = p.ws;
;     float* rowss = (float*)(ws + O_ROWSS);
;     bf16_t* XG = (bf16_t*)(ws + O_XG); bf16_t* MIXA = (bf16_t*)(ws + O_MIXA); bf16_t* HB = (bf16_t*)(ws + O_H);
;     float* XC = (float*)(ws + O_XC);
;     volatile LAS unsigned* bst = (volatile LAS unsigned*)(lds + 131072 + 1024);
;     if (threadIdx.x == 0) { bst[0] = 0u; bst[1] = 0u; }
;     __syncthreads();
;     XcdBarrier xbar; xbar.bar = (unsigned*)(ws + O_BAR); xbar.x = 0; xbar.st = bst;
_Z6mk_fwd6Params:
	s_load_dwordx4 s[8:11], s[0:1], 0xc8
	s_mov_b32 s20, s2
	s_add_u32 s2, s0, 0xd0
	s_addc_u32 s3, s1, 0
	v_and_b32_e32 v211, 0x3ff, v0
	v_writelane_b32 v255, 0, 63
	v_writelane_b32 v252, s2, 0
	v_cmp_eq_u32_e64 s[4:5], 0, v211
	s_nop 0
	v_writelane_b32 v252, s3, 1
	s_mov_b64 s[2:3], exec
	v_writelane_b32 v252, s4, 2
	s_nop 1
	v_writelane_b32 v252, s5, 3
	s_and_b64 s[4:5], s[2:3], s[4:5]
	s_mov_b64 exec, s[4:5]
	s_cbranch_execz .LBB0_2
	s_add_i32 s4, 0, 0x20400
	v_mov_b32_e32 v1, 0
	v_mov_b32_e32 v2, s4
	s_add_i32 s4, 0, 0x20404
	ds_write_b32 v2, v1
	v_mov_b32_e32 v2, s4
	ds_write_b32 v2, v1

; template <class Epi, class Sched, bool ALIGN_EPI = false, bool SP2 = false>
; __device__ __forceinline__ void gemm_phase(PG8_LAS unsigned char* lds, const Gemm g, const Sched& S, const Epi& E) {
;     ...
;     for (int i = 0; i < 2; ++i) { int R, C; stage_rc(tid * 16 + i * 8192, R, C); const int Rb = Epi::PERM ? ((R & ~31) + perm32(R & 31)) : R;
;         voffA[i] = (unsigned)(R * LD + C) * 2u; voffB[i] = (unsigned)(Rb * LD + C) * 2u; }
;     const size_t kstep = (size_t)(BK * 2);
;     const size_t hstep = (size_t)HALF * LD * 2;
;     const size_t tstep = 2 * hstep;
;     const unsigned ldsw = (unsigned)wid * 1024u;
;     const int aoff = lds_byte(wr * 64 + fr, fq * 8), boff = lds_byte(wc * 32 + fr, fq * 8);
;     ...
;     Unit cur, nxt; int ui = 0;
;     if (!S.next(0, cur)) return;
;     f32x4 acc[2][2][4][2];
; #pragma unroll
;     for (int a = 0; a < 2; ++a)
; #pragma unroll
;         for (int b = 0; b < 2; ++b)
; #pragma unroll
;             for (int m = 0; m < 4; ++m)
; #pragma unroll
;                 for (int n = 0; n < 2; ++n) acc[a][b][m][n] = (f32x4){0.f, 0.f, 0.f, 0.f};
;     bf16x8 At[4][2], B0[2][2], B1[2][2];
;     const char* cA = (const char*)g.A + (size_t)cur.pm * tstep; const char* cB = (const char*)g.Bt + (size_t)cur.pn * tstep;
;     S.a_ready(cur);
;     if constexpr (SP2) {
;         PG8_STAGE(PG8_SB(0, 0), cB, voffB); PG8_STAGE(PG8_SB(0, 1), cB + hstep, voffB); PG8_STAGE(PG8_SA(0, 0), cA, voffA); PG8_STAGE(PG8_SA(0, 1), cA + hstep, voffA);
;         if (wr == 1) PG8_BAR;
; __global__ void __launch_bounds__(NTHR, 2) mk_fwd(Params p) {
;     ...
;             const int gsite = l * 3 + sub, nsite = gsite + 1; const bool fin = (nsite == 12);
;             const int M = (lastl && sub >= 1) ? ML : MT;
;             const bf16_t* A = (sub == 1 && (l & 1) == 0) ? MIXA : HB; const int K = sub == 1 ? 1024 : HP;
;             const bf16_t* Bt = (const bf16_t*)(wl + (sub == 0 ? W_D1 : (sub == 2 ? W_D2 : W_MIX + 2 * SZ_WM)));
;             EpiRes E{p.out, XC, (const float*)(ws + O_GT) + (size_t)gsite * 9 * 1024, fin ? nullptr : (const float*)(ws + O_GS) + (size_t)nsite * 9 * 1024, XG, rowss + (size_t)nsite * MT,
;                      gsite == 0 ? p.in[I_X] : (const float*)p.out, gsite == 0 ? p.in[I_CTX] : (const float*)XC};
;             const bool split = (sub != 1 && M == MT);
;             run_gemm<EpiRes>(lds, A, Bt, split ? ML : M, 1024, K, 0, E);
.LBB0_527:
	s_add_i32 s3, s16, 1
	s_mul_i32 s1, s3, 0x9000
	v_readlane_b32 s28, v253, 17
	s_mul_hi_u32 s0, s3, 0x9000
	v_readlane_b32 s29, v253, 18
	s_add_u32 s85, s28, s1
	s_addc_u32 s86, s29, s0
	s_cmp_eq_u32 s3, 12
	s_cselect_b64 s[0:1], -1, 0
	s_cmp_lg_u32 s3, 12
	v_writelane_b32 v255, s0, 30
	s_cselect_b64 s[58:59], -1, 0
	s_bitcmp0_b32 s10, 0
	v_writelane_b32 v255, s1, 31
	s_cselect_b64 s[0:1], -1, 0
	s_and_b64 s[0:1], s[90:91], s[0:1]
	s_and_b64 s[0:1], s[0:1], exec
	v_readlane_b32 s0, v254, 39
	v_readlane_b32 s4, v254, 41
	v_readlane_b32 s1, v254, 40
	v_readlane_b32 s5, v254, 42
	v_writelane_b32 v255, s10, 32
	s_cselect_b32 s1, s5, s1
	v_writelane_b32 v255, s1, 33
	s_cselect_b32 s0, s4, s0
	v_writelane_b32 v255, s0, 34
	s_add_u32 s0, s11, s6
	v_writelane_b32 v255, s0, 19
	s_addc_u32 s0, s88, s7
	s_mul_i32 s1, s16, 0x9000
	v_readlane_b32 s20, v253, 15
	v_writelane_b32 v255, s0, 35
	s_add_u32 s1, s20, s1
	s_mul_hi_u32 s0, s16, 0x9000
	v_writelane_b32 v255, s1, 36
	v_readlane_b32 s1, v253, 16
	s_addc_u32 s0, s1, s0
	s_cmp_eq_u32 s16, 0
	s_mov_b32 s95, s11
	v_writelane_b32 v255, s0, 37
	s_mov_b32 s94, s16
	s_cselect_b64 s[0:1], -1, 0
	v_readlane_b32 s4, v253, 62
	s_and_b64 s[28:29], s[0:1], exec
	v_readlane_b32 s20, v252, 12
	v_readlane_b32 s9, v254, 3
	v_readlane_b32 s8, v254, 2
	s_cselect_b32 s57, s9, s20
	v_readlane_b32 s20, v252, 11
	s_mov_b64 s[34:35], s[90:91]
	s_mul_hi_u32 s97, s3, 0x22000
	s_cselect_b32 s56, s8, s20
	v_readlane_b32 s10, v255, 63
	s_cmp_eq_u32 s10, 0
	s_cbranch_scc0 .Lres_hookA_done
	s_mov_b32 s10, 1
	s_nop 0
	v_writelane_b32 v255, s10, 63
	v_readlane_b32 s11, v254, 43
	s_bitcmp1_b32 s11, 5
	s_cbranch_scc0 .Lres_hookA_done
	s_mov_b64 s[38:39], 0
.Lres_hookA_done:
	s_andn2_b64 vcc, exec, s[38:39]
	s_mul_i32 s9, s3, 0x22000
	v_readlane_b32 s5, v253, 63
	v_readlane_b32 s6, v254, 0
	v_readlane_b32 s7, v254, 1
	v_readlane_b32 s10, v254, 4
	v_readlane_b32 s11, v254, 5
	v_readlane_b32 s12, v254, 6
	v_readlane_b32 s13, v254, 7
	v_readlane_b32 s14, v254, 8
	v_readlane_b32 s15, v254, 9
	v_readlane_b32 s16, v254, 10
	v_readlane_b32 s17, v254, 11
	v_readlane_b32 s18, v254, 12
	v_readlane_b32 s19, v254, 13
	s_cbranch_vccnz .LBB0_604
	v_bfe_i32 v2, v12, 27, 1
	v_lshlrev_b32_e32 v0, 4, v12
	v_lshrrev_b32_e32 v2, 22, v2
	v_add_u32_e32 v2, v0, v2
	v_and_b32_e32 v2, 0xfffffc00, v2
	s_waitcnt lgkmcnt(0)
	v_ashrrev_i32_e32 v1, 31, v12
	v_sub_u32_e32 v2, v0, v2
	v_lshrrev_b32_e32 v1, 26, v1
	v_lshrrev_b32_e32 v3, 4, v2
	v_add_u32_e32 v1, v12, v1
	v_bitop3_b32 v3, v3, v2, 32 bitop3:0x6c
	v_ashrrev_i32_e32 v2, 31, v2
	v_ashrrev_i32_e32 v1, 6, v1
	v_lshrrev_b32_e32 v2, 26, v2
	v_lshlrev_b32_e32 v4, 3, v1
	v_add_u32_e32 v2, v3, v2
	v_and_b32_e32 v4, -16, v4
	v_ashrrev_i32_e32 v2, 6, v2
	v_lshlrev_b32_e32 v1, 5, v1
	s_and_b64 s[28:29], s[34:35], exec
	s_movk_i32 s3, 0xb00
	v_add_u32_e32 v4, v2, v4
	v_and_b32_e32 v13, 32, v1
	v_mul_i32_i24_e32 v1, 64, v2
	s_cselect_b32 s27, 0x400, s3
	v_sub_u32_e32 v1, v3, v1
	v_lshlrev_b32_e32 v3, 1, v4
	v_lshrrev_b32_e32 v5, 2, v4
	v_and_b32_e32 v2, 3, v2
	s_mov_b32 s3, 0xffffe0
	v_ashrrev_i16_sdwa v1, v244, sext(v1) dst_sel:DWORD dst_unused:UNUSED_PAD src0_sel:DWORD src1_sel:BYTE_0
	v_and_b32_e32 v3, 24, v3
	v_and_b32_e32 v5, 4, v5
	v_and_or_b32 v2, v4, s3, v2
	v_bfe_i32 v14, v1, 0, 16
	v_or3_b32 v2, v2, v5, v3
	v_add_u32_e32 v1, v13, v14
	v_mul_lo_u32 v15, v4, s27
	v_mul_u32_u24_e32 v2, s27, v2
	v_add_u32_e32 v0, 0x2000, v0
	v_add_lshl_u32 v222, v1, v15, 1
	v_add_lshl_u32 v208, v2, v1, 1
	v_ashrrev_i32_e32 v1, 31, v0
	v_lshrrev_b32_e32 v1, 22, v1
	v_add_u32_e32 v1, v0, v1
	v_ashrrev_i32_e32 v1, 10, v1
	v_mul_i32_i24_e32 v2, 0x400, v1
	v_sub_u32_e32 v0, v0, v2
	v_lshrrev_b32_e32 v2, 4, v0
	v_bitop3_b32 v0, v2, v0, 32 bitop3:0x6c
	v_ashrrev_i32_e32 v3, 31, v0
	v_lshrrev_b32_e32 v3, 26, v3
	v_writelane_b32 v255, s40, 38
	v_lshlrev_b32_e32 v2, 3, v1
	v_add_u32_e32 v3, v0, v3
	v_writelane_b32 v255, s41, 39
	s_ashr_i32 s30, s43, 6
	v_and_b32_e32 v2, -16, v2
	v_ashrrev_i32_e32 v4, 6, v3
	v_lshlrev_b32_e32 v1, 5, v1
	s_lshl_b32 s74, s27, 9
	v_add_u32_e32 v2, v4, v2
	v_and_b32_e32 v16, 32, v1
	v_and_b32_e32 v1, 0xc0, v3
	s_ashr_i32 s34, s43, 8
	s_lshl_b32 s63, s30, 10
	s_lshl_b32 s66, s27, 8
	s_mul_i32 s29, s74, s82
	v_readlane_b32 s2, v255, 19
	v_sub_u32_e32 v0, v0, v1
	v_lshlrev_b32_e32 v1, 1, v2
	v_lshrrev_b32_e32 v3, 2, v2
	v_and_b32_e32 v4, 3, v4
	s_mul_hi_i32 s28, s74, s82
	s_add_u32 s80, s2, s29
	v_readlane_b32 s2, v255, 35
	v_ashrrev_i16_sdwa v0, v244, sext(v0) dst_sel:DWORD dst_unused:UNUSED_PAD src0_sel:DWORD src1_sel:BYTE_0
	v_and_b32_e32 v1, 24, v1
	v_and_b32_e32 v3, 4, v3
	v_and_or_b32 v4, v2, s3, v4
	s_addc_u32 s81, s2, s28
	s_add_i32 s75, s63, 0
	v_bfe_i32 v17, v0, 0, 16
	v_or3_b32 v1, v4, v3, v1
	s_add_i32 m0, s75, 0x10000
	v_add_u32_e32 v0, v16, v17
	v_mul_u32_u24_e32 v1, s27, v1
	global_load_lds_dwordx4 v208, s[80:81]
	s_add_i32 m0, s75, 0x12000
	v_add_lshl_u32 v226, v1, v0, 1
	s_add_u32 s28, s80, s66
	global_load_lds_dwordx4 v226, s[80:81]
	s_addc_u32 s29, s81, 0
	s_add_i32 m0, s75, 0x14000
	s_mul_i32 s35, s74, s42
	global_load_lds_dwordx4 v208, s[28:29]
	s_add_i32 m0, s75, 0x16000
	v_readlane_b32 s2, v255, 34
	s_mul_hi_i32 s3, s74, s42
	s_add_u32 s40, s2, s35
	v_readlane_b32 s2, v255, 33
	v_mov_b32_e32 v227, v209
	s_addc_u32 s41, s2, s3
	s_add_i32 s50, s75, 0x2000
	v_mul_lo_u32 v18, v2, s27
	v_lshl_add_u64 v[4:5], s[28:29], 0, v[208:209]
	v_lshl_add_u64 v[6:7], s[28:29], 0, v[226:227]
	global_load_lds_dwordx4 v226, s[28:29]
	s_mov_b32 m0, s75
	s_add_u32 s28, s40, s66
	v_add_lshl_u32 v224, v0, v18, 1
	global_load_lds_dwordx4 v222, s[40:41]
	s_mov_b32 m0, s50
	s_addc_u32 s29, s41, 0
	s_add_i32 s68, s75, 0x4000
	global_load_lds_dwordx4 v224, s[40:41]
	s_mov_b32 m0, s68
	s_add_i32 s69, s75, 0x6000
	global_load_lds_dwordx4 v222, s[28:29]
	s_mov_b32 m0, s69
	s_cmp_eq_u32 s34, 1
	global_load_lds_dwordx4 v224, s[28:29]
	s_cselect_b64 s[2:3], -1, 0
	v_mov_b32_e32 v223, v209
	v_mov_b32_e32 v225, v209
	v_writelane_b32 v255, s2, 40
	s_mov_b32 s67, s73
	v_lshl_add_u64 v[0:1], s[80:81], 0, v[208:209]
	v_lshl_add_u64 v[2:3], s[80:81], 0, v[226:227]
	v_lshl_add_u64 v[8:9], s[40:41], 0, v[222:223]
	v_lshl_add_u64 v[10:11], s[40:41], 0, v[224:225]
	v_writelane_b32 v255, s3, 41
	s_cmp_lg_u32 s34, 1
	s_cbranch_scc1 .LBB0_530
	s_barrier

; __device__ __forceinline__ int opaque_tid() { int t = (int)threadIdx.x; asm volatile("" : "+v"(t)); return t; }
;     __device__ __forceinline__ void operator()(const f32x4 (&acc)[2][2][4][2], const Unit& u, int wr, int wc, int fr_, int fq_) const {
;         const int tl_ = opaque_tid(); const int fr = tl_ & 15, fq = (tl_ >> 4) & 3; (void)fr_; (void)fq_;
;         const int mb = mb_of_panel(u.pm);
;         float* xb = u.pm < 128 ? xl + (size_t)u.pm * 256 * 1024 : xc + (size_t)(u.pm - 128) * 256 * 1024;
;         const float* xib = u.pm < 128 ? xil + (size_t)u.pm * 256 * 1024 : xic + (size_t)(u.pm - 128) * 256 * 1024;
;         const int lr0 = wr * 64 + fr, col0 = u.pn * 256 + wc * 32 + 8 * fq;
;         float* xbase = xb + (size_t)lr0 * 1024 + col0; const float* xibase = xib + (size_t)lr0 * 1024 + col0;
;         bf16_t* gbase = xg + ((size_t)u.pm * 256 + lr0) * 1024 + col0;
;         float ss[4];
;         f32x4 xa[4][2], xbf[4][2];
.LBB0_544:
	s_nop 7
	v_readlane_b32 s3, v255, 63
	s_cmp_eq_u32 s3, 1
	s_cbranch_scc0 .Lres_nozero
	v_mov_b32_e32 v0, 0
	v_mov_b32_e32 v1, 0
	v_mov_b32_e32 v2, 0
	v_mov_b32_e32 v3, 0
	v_mov_b32_e32 v4, 0
	v_mov_b32_e32 v5, 0
	v_mov_b32_e32 v6, 0
	v_mov_b32_e32 v7, 0
	v_mov_b32_e32 v8, 0
	v_mov_b32_e32 v9, 0
	v_mov_b32_e32 v10, 0
	v_mov_b32_e32 v11, 0
	v_mov_b32_e32 v12, 0
	v_mov_b32_e32 v13, 0
	v_mov_b32_e32 v14, 0
	v_mov_b32_e32 v15, 0
	v_mov_b32_e32 v16, 0
	v_mov_b32_e32 v17, 0
	v_mov_b32_e32 v18, 0
	v_mov_b32_e32 v19, 0
	v_mov_b32_e32 v20, 0
	v_mov_b32_e32 v21, 0
	v_mov_b32_e32 v22, 0
	v_mov_b32_e32 v23, 0
	v_mov_b32_e32 v24, 0
	v_mov_b32_e32 v25, 0
	v_mov_b32_e32 v26, 0
	v_mov_b32_e32 v27, 0
	v_mov_b32_e32 v28, 0
	v_mov_b32_e32 v29, 0
	v_mov_b32_e32 v30, 0
	v_mov_b32_e32 v31, 0
	v_mov_b32_e32 v32, 0
	v_mov_b32_e32 v33, 0
	v_mov_b32_e32 v34, 0
	v_mov_b32_e32 v35, 0
	v_mov_b32_e32 v36, 0
	v_mov_b32_e32 v37, 0
	v_mov_b32_e32 v38, 0
	v_mov_b32_e32 v39, 0
	v_mov_b32_e32 v40, 0
	v_mov_b32_e32 v41, 0
	v_mov_b32_e32 v42, 0
	v_mov_b32_e32 v43, 0
	v_mov_b32_e32 v44, 0
	v_mov_b32_e32 v45, 0
	v_mov_b32_e32 v46, 0
	v_mov_b32_e32 v47, 0
	v_mov_b32_e32 v48, 0
	v_mov_b32_e32 v49, 0
	v_mov_b32_e32 v50, 0
	v_mov_b32_e32 v51, 0
	v_mov_b32_e32 v52, 0
	v_mov_b32_e32 v53, 0
	v_mov_b32_e32 v54, 0
	v_mov_b32_e32 v55, 0
	v_mov_b32_e32 v56, 0
	v_mov_b32_e32 v57, 0
	v_mov_b32_e32 v58, 0
	v_mov_b32_e32 v59, 0
	v_mov_b32_e32 v60, 0
	v_mov_b32_e32 v61, 0
	v_mov_b32_e32 v62, 0
	v_mov_b32_e32 v63, 0
	v_mov_b32_e32 v64, 0
	v_mov_b32_e32 v65, 0
	v_mov_b32_e32 v66, 0
	v_mov_b32_e32 v67, 0
	v_mov_b32_e32 v68, 0
	v_mov_b32_e32 v69, 0
	v_mov_b32_e32 v70, 0
	v_mov_b32_e32 v71, 0
	v_mov_b32_e32 v72, 0
	v_mov_b32_e32 v73, 0
	v_mov_b32_e32 v74, 0
	v_mov_b32_e32 v75, 0
	v_mov_b32_e32 v76, 0
	v_mov_b32_e32 v77, 0
	v_mov_b32_e32 v78, 0
	v_mov_b32_e32 v79, 0
	v_mov_b32_e32 v80, 0
	v_mov_b32_e32 v81, 0
	v_mov_b32_e32 v82, 0
	v_mov_b32_e32 v83, 0
	v_mov_b32_e32 v84, 0
	v_mov_b32_e32 v85, 0
	v_mov_b32_e32 v86, 0
	v_mov_b32_e32 v87, 0
	v_mov_b32_e32 v88, 0
	v_mov_b32_e32 v89, 0
	v_mov_b32_e32 v90, 0
	v_mov_b32_e32 v91, 0
	v_mov_b32_e32 v92, 0
	v_mov_b32_e32 v93, 0
	v_mov_b32_e32 v94, 0
	v_mov_b32_e32 v95, 0
	v_mov_b32_e32 v96, 0
	v_mov_b32_e32 v97, 0
	v_mov_b32_e32 v98, 0
	v_mov_b32_e32 v99, 0
	v_mov_b32_e32 v100, 0
	v_mov_b32_e32 v101, 0
	v_mov_b32_e32 v102, 0
	v_mov_b32_e32 v103, 0
	v_mov_b32_e32 v104, 0
	v_mov_b32_e32 v105, 0
	v_mov_b32_e32 v106, 0
	v_mov_b32_e32 v107, 0
	v_mov_b32_e32 v108, 0
	v_mov_b32_e32 v109, 0
	v_mov_b32_e32 v110, 0
	v_mov_b32_e32 v111, 0
	v_mov_b32_e32 v112, 0
	v_mov_b32_e32 v113, 0
	v_mov_b32_e32 v114, 0
	v_mov_b32_e32 v115, 0
	v_mov_b32_e32 v116, 0
	v_mov_b32_e32 v117, 0
	v_mov_b32_e32 v118, 0
	v_mov_b32_e32 v119, 0
	v_mov_b32_e32 v120, 0
	v_mov_b32_e32 v121, 0
	v_mov_b32_e32 v122, 0
	v_mov_b32_e32 v123, 0
	v_mov_b32_e32 v124, 0
	v_mov_b32_e32 v125, 0
	v_mov_b32_e32 v126, 0
	v_mov_b32_e32 v127, 0

.LBB0_564:
	s_nop 1
	v_mul_f32_e32 v128, v137, v137
	v_mul_f32_e32 v129, v139, v139
	v_mul_f32_e32 v89, v89, v89
	v_fmac_f32_e32 v128, v136, v136
	v_fmac_f32_e32 v129, v138, v138
	v_mul_f32_e32 v93, v93, v93
	v_fmac_f32_e32 v89, v88, v88
	v_mul_f32_e32 v88, v91, v91
	v_add_f32_e32 v128, v128, v129
	v_mul_f32_e32 v129, v145, v145
	v_mul_f32_e32 v130, v147, v147
	v_fmac_f32_e32 v93, v92, v92
	v_mul_f32_e32 v92, v95, v95
	v_fmac_f32_e32 v88, v90, v90
	v_and_b32_e32 v90, 64, v246
	v_fmac_f32_e32 v129, v144, v144
	v_fmac_f32_e32 v130, v146, v146
	v_fmac_f32_e32 v92, v94, v94
	v_add_f32_e32 v88, v89, v88
	v_xor_b32_e32 v89, 16, v246
	v_add_u32_e32 v90, 64, v90
	v_add_f32_e32 v129, v129, v130
	v_add_f32_e32 v92, v93, v92
	v_cmp_lt_i32_e32 vcc, v89, v90
	v_add_f32_e32 v128, v128, v129
	v_add_f32_e32 v88, v92, v88
	v_cndmask_b32_e32 v89, v246, v89, vcc
	v_add_f32_e32 v88, v128, v88
	v_lshlrev_b32_e32 v144, 2, v89
	ds_bpermute_b32 v89, v144, v88
	v_xor_b32_e32 v91, 32, v246
	v_cmp_lt_i32_e32 vcc, v91, v90
	v_cmp_eq_u32_e64 s[42:43], 0, v215
	s_waitcnt lgkmcnt(0)
	v_add_f32_e32 v88, v88, v89
	v_cndmask_b32_e32 v90, v246, v91, vcc
	v_readlane_b32 s46, v255, 63
	s_cmp_eq_u32 s46, 1
	s_cselect_b64 s[42:43], 0, s[42:43]
	v_lshlrev_b32_e32 v145, 2, v90
	ds_bpermute_b32 v89, v145, v88
	s_lshl_b64 s[82:83], s[82:83], 10
	s_and_saveexec_b64 s[46:47], s[42:43]
	s_cbranch_execz .LBB0_566
	s_add_u32 s28, s84, s82
	s_addc_u32 s29, s62, s83
	v_lshl_add_u64 v[90:91], v[232:233], 2, s[28:29]
	s_waitcnt lgkmcnt(0)
	v_add_f32_e32 v88, v88, v89
	global_atomic_add_f32 v[90:91], v88, off

; __global__ void __launch_bounds__(NTHR, 2) mk_fwd(Params p) {
;     ...
;             const bool split = (sub != 1 && M == MT);
;             run_gemm<EpiRes>(lds, A, Bt, split ? ML : M, 1024, K, 0, E);
;             if (split) {
;                 float* slab = (float*)(ws + O_MIXA);
;                 for (int q = 0; q < 4; ++q) { const int k0 = (q >> 1) * 1408 + (q & 1) * 640, len = (q & 1) ? 768 : 640;
;                     EpiPart EP{slab + (size_t)q * MC * 1024, 1024};
;                     run_gemm<EpiPart>(lds, A + (size_t)ML * HP + k0, Bt + k0, MC, 1024, len, 64 * q, EP, HP); }
;                 xcd_barrier(xbar);
.LBB0_604:
	v_readlane_b32 s0, v255, 63
	s_cmp_eq_u32 s0, 1
	s_cselect_b64 s[0:1], -1, 0
	s_or_b64 s[0:1], s[0:1], s[34:35]
	s_or_b64 s[0:1], s[0:1], s[40:41]
	v_readlane_b32 s18, v255, 23
	v_readlane_b32 s12, v255, 21
	v_readlane_b32 s14, v255, 26
	s_mov_b32 s8, s97
	s_and_b64 vcc, exec, s[0:1]
	v_readlane_b32 s97, v254, 30
	s_mov_b32 s64, 0x1ffff
	v_readlane_b32 s20, v254, 43
	v_readlane_b32 s17, v255, 25
	v_readlane_b32 s19, v255, 24
	v_readlane_b32 s10, v255, 32
	v_readlane_b32 s13, v255, 22
	s_mov_b32 s11, s95
	v_readlane_b32 s15, v255, 27
	s_mov_b32 s16, s94
	s_cbranch_vccnz .LBB0_689
	v_readlane_b32 s0, v255, 34
	s_add_u32 s2, s0, 0xb000000
	v_readlane_b32 s0, v255, 33
	s_addc_u32 s27, s0, 0
	s_mov_b32 s34, 0
	s_branch .LBB0_608

; __global__ void __launch_bounds__(NTHR, 2) mk_fwd(Params p) {
;     ...
;     for (int s = p.st_lo; s < p.st_hi; ++s) {
;         int kind, l, sub; decode_stage(s, kind, l, sub);
;     ...
;         if (s + 1 < p.st_hi) { if (s == p.st_lo) { grid.sync(); xbar = xcd_barrier_post((unsigned*)(ws + O_BAR), bst); } else xcd_barrier(xbar); }
;     }
.LBB0_905:
	v_readlane_b32 s3, v254, 44
	v_readlane_b32 s4, v252, 4
	s_add_i32 s2, s3, 1
	v_readlane_b32 s5, v252, 5
	v_readlane_b32 s0, v255, 63
	s_cmp_eq_u32 s0, 1
	s_cbranch_scc1 .Ltail_pass1
	s_mov_b32 s0, 0
	s_nop 0
	v_writelane_b32 v255, s0, 63
	s_mov_b32 s89, s67
	s_cmp_ge_i32 s2, s5
	s_mov_b64 s[0:1], -1
	v_readlane_b32 s62, v254, 39
	v_readlane_b32 s66, v254, 41
	v_readlane_b32 s6, v252, 6
	v_readlane_b32 s7, v252, 7
	v_readlane_b32 s63, v254, 40
	v_readlane_b32 s67, v254, 42
	s_cbranch_scc0 .LBB0_906
	s_getpc_b64 s[98:99]

; __global__ void __launch_bounds__(NTHR, 2) mk_fwd(Params p) {
;     ...
;     for (int s = p.st_lo; s < p.st_hi; ++s) {
;         int kind, l, sub; decode_stage(s, kind, l, sub);
.Ltail_pass1:
	s_mov_b32 s0, 2
	s_nop 0
	v_writelane_b32 v255, s0, 63
	s_mov_b32 s2, s3
	s_mov_b32 s89, s67
	v_readlane_b32 s62, v254, 39
	v_readlane_b32 s66, v254, 41
	v_readlane_b32 s6, v252, 6
	v_readlane_b32 s7, v252, 7
	v_readlane_b32 s63, v254, 40
	v_readlane_b32 s67, v254, 42
	v_readlane_b32 s24, v254, 33
	v_readlane_b32 s25, v254, 34
	s_mov_b64 s[0:1], 0
	s_branch .LBB0_956
